# MLA KV loop unrolled x2 (K buffer parity as immediates), K/V global addresses advanced on the scalar unit: 6 fewer VALU per tile; plus earlier diet and hook reorder
# speedup vs baseline: 1.0058x; 1.0058x over previous
; template <int DQK, int DV, int RH, bool NEGM> ...
;     ...
;     const int NT = nkv / 64;
;     AT_GLOAD(0); AT_LSTORE(0, 0); __syncthreads();
;     int vs_prev = 2, vs_cur = 0, vs_next = 1;
;     if (!grpB) {
;         for (int t = 0; t < NT; ++t) {
;             const int kb = t & 1;
;             if (t + 1 < NT) AT_GLOAD(t + 1);
.LBB0_881:
	s_or_b64 exec, exec, s[42:43]
	v_pk_add_f32 v[48:49], v[48:49], v[54:55]
	v_pk_add_f32 v[64:65], v[128:129], v[64:65]
	v_pk_add_f32 v[48:49], v[58:59], v[48:49] op_sel_hi:[0,1]
	v_pk_add_f32 v[52:53], v[52:53], v[56:57]
	v_pk_add_f32 v[48:49], v[64:65], v[48:49]
	v_pk_add_f32 v[70:71], v[118:119], v[70:71]
	v_pk_add_f32 v[48:49], v[52:53], v[48:49]
	v_add_u32_e32 v54, v136, v135
	v_pk_add_f32 v[150:151], v[70:71], v[48:49]
	v_add_u32_e32 v48, 0x8c00, v166
	s_waitcnt vmcnt(0)
	ds_write2_b64 v48, v[74:75], v[76:77] offset1:2
	v_mul_lo_u32 v48, v54, 12
	v_sub_u32_e32 v52, v133, v48
	s_lshr_b32 s21, s61, 4
	v_lshlrev_b32_e32 v48, 3, v52
	v_lshlrev_b32_e32 v175, 4, v52
	v_mov_b64_e32 v[52:53], s[40:41]
	s_and_b32 s42, s21, 7
	v_mul_lo_u32 v174, v54, s56
	v_mad_i64_i32 v[54:55], s[40:41], v54, s51, v[52:53]
	v_pk_add_f32 v[50:51], v[50:51], v[62:63]
	v_ashrrev_i32_e32 v49, 31, v48
	v_mad_u64_u32 v[54:55], s[40:41], s42, v163, v[54:55]
	v_pk_add_f32 v[66:67], v[130:131], v[66:67]
	v_pk_add_f32 v[50:51], v[58:59], v[50:51] op_sel_hi:[0,1]
	v_lshl_add_u64 v[48:49], v[48:49], 1, v[54:55]
	v_pk_add_f32 v[56:57], v[116:117], v[68:69]
	v_pk_add_f32 v[50:51], v[66:67], v[50:51]
	v_mov_b32_e32 v154, v48
	v_mad_i64_i32 v[48:49], s[40:41], v59, s51, v[52:53]
	v_pk_add_f32 v[60:61], v[60:61], v[72:73]
	v_pk_add_f32 v[50:51], v[56:57], v[50:51]
	s_lshl_b32 s43, s42, 6
	v_mad_u64_u32 v[48:49], s[40:41], s42, v163, v[48:49]
	v_pk_add_f32 v[152:153], v[60:61], v[50:51]
	v_lshlrev_b32_e32 v50, 3, v112
	s_add_i32 s40, s47, s43
	v_ashrrev_i32_e32 v51, 31, v50
	s_ashr_i32 s41, s40, 31
	v_lshl_add_u64 v[48:49], v[50:51], 1, v[48:49]
	s_lshl_b64 s[40:41], s[40:41], 13
	v_and_b32_e32 v50, 7, v132
	v_mov_b32_e32 v156, v48
	v_lshl_add_u64 v[48:49], v[78:79], 0, s[40:41]
	v_lshlrev_b32_e32 v148, 4, v50
	v_lshl_add_u64 v[48:49], v[48:49], 0, v[148:149]
	v_mul_u32_u24_e32 v173, 0x90, v134
	s_mov_b32 s21, 1
	v_mov_b32_e32 v158, v48
	s_mov_b32 s42, 2
	s_mov_b32 s43, 1
	s_waitcnt lgkmcnt(0)
	s_barrier
	s_mov_b64 s[98:99], s[28:29]
	s_mov_b64 s[100:101], s[30:31]
	v_add_u32_e32 v244, v174, v175
	v_add_u32_e32 v245, v171, v172
	s_branch .Lmla_odd

.Lmla_odd:
	global_load_dwordx4 v[104:107], v154, s[98:99]
	s_mov_b64 exec, s[8:9]
	global_load_dwordx4 v[108:111], v156, s[98:99]
	s_mov_b64 exec, -1
	global_load_dwordx4 v[112:115], v158, s[100:101]
	s_add_u32 s98, s98, 0x18000
	s_addc_u32 s99, s99, 0
	s_add_u32 s100, s100, 0x80
	s_addc_u32 s101, s101, 0
	ds_read_b128 v[48:51], v169 offset:13312
	ds_read_b128 v[52:55], v169 offset:13344
	ds_read_b128 v[116:119], v169 offset:19968
	ds_read_b128 v[120:123], v169 offset:20000
	s_waitcnt lgkmcnt(3)
	v_mfma_f32_32x32x16_bf16 v[64:79], v[48:51], v[100:103], v[32:47]
	ds_read_b128 v[124:127], v169 offset:13376
	ds_read_b128 v[128:131], v169 offset:13408
	ds_read_b128 v[132:135], v169 offset:20032
	ds_read_b128 v[136:139], v169 offset:20064
	s_waitcnt lgkmcnt(4)
	v_mfma_f32_32x32x16_bf16 v[64:79], v[52:55], v[96:99], v[64:79]
	v_mfma_f32_32x32x16_bf16 v[48:63], v[116:119], v[100:103], v[32:47]
	v_mfma_f32_32x32x16_bf16 v[48:63], v[120:123], v[96:99], v[48:63]
	s_waitcnt lgkmcnt(1)
	v_mfma_f32_32x32x16_bf16 v[64:79], v[124:127], v[92:95], v[64:79]
	v_mfma_f32_32x32x16_bf16 v[48:63], v[132:135], v[92:95], v[48:63]
	v_mfma_f32_32x32x16_bf16 v[64:79], v[128:131], v[88:91], v[64:79]
	ds_read_b128 v[116:119], v169 offset:13440
	ds_read_b128 v[120:123], v169 offset:13472
	ds_read_b128 v[128:131], v169 offset:20096
	ds_read_b128 v[176:179], v169 offset:20128
	s_waitcnt lgkmcnt(3)
	v_mfma_f32_32x32x16_bf16 v[48:63], v[136:139], v[88:91], v[48:63]
	v_mfma_f32_32x32x16_bf16 v[64:79], v[116:119], v[84:87], v[64:79]
	s_mulk_i32 s21, 0x2400
	v_add_u32_e32 v116, s21, v170
	ds_read_b128 v[136:139], v116 offset:26624
	ds_read_b128 v[124:127], v116 offset:26656
	s_waitcnt lgkmcnt(3)
	v_mfma_f32_32x32x16_bf16 v[48:63], v[128:131], v[84:87], v[48:63]
	v_mfma_f32_32x32x16_bf16 v[64:79], v[120:123], v[80:83], v[64:79]
	ds_read_b128 v[132:135], v116 offset:26688
	ds_read_b128 v[120:123], v116 offset:26720
	ds_read_b128 v[144:147], v116 offset:31232
	ds_read_b128 v[140:143], v116 offset:31264
	ds_read_b128 v[128:131], v116 offset:31296
	ds_read_b128 v[116:119], v116 offset:31328
	s_waitcnt lgkmcnt(8)
	v_mfma_f32_32x32x16_bf16 v[48:63], v[176:179], v[80:83], v[48:63]
	s_add_i32 s43, s43, 1
	s_nop 10
	v_max_f32_e32 v148, v64, v48
	v_max_f32_e32 v160, v65, v49
	v_max_f32_e32 v161, v67, v51
	v_max3_f32 v176, v66, v50, v70
	v_max3_f32 v161, v161, v71, v55
	v_max3_f32 v148, v148, v68, v52
	v_max3_f32 v160, v160, v69, v53
	v_max3_f32 v176, v176, v54, v74
	v_max3_f32 v161, v161, v75, v59
	v_max3_f32 v148, v148, v72, v56
	v_max3_f32 v160, v160, v73, v57
	v_max3_f32 v176, v176, v58, v78
	v_max3_f32 v161, v161, v79, v63
	v_max3_f32 v148, v148, v76, v60
	v_max3_f32 v160, v160, v77, v61
	v_max3_f32 v161, v176, v62, v161
	v_max3_f32 v148, v148, v160, v161
	v_mov_b32_e32 v160, v148
	s_nop 1
	v_permlane32_swap_b32_e32 v148, v160
	v_max_f32_e32 v148, v148, v160
	v_cmp_lt_f32_e32 vcc, s59, v148
	s_cbranch_vccz .Lmla_norescale_o
	v_max_f32_e32 v32, v148, v148
	v_max_f32_e32 v148, 0, v32
	v_exp_f32_e64 v160, -v148
	v_add_f32_e32 v168, v168, v148
	v_xor_b32_e32 v32, 0x80000000, v168
	v_mov_b32_e32 v33, v32
	v_mov_b32_e32 v34, v32
	v_mov_b32_e32 v35, v32
	v_mov_b32_e32 v36, v32
	v_mov_b32_e32 v37, v32
	v_mov_b32_e32 v38, v32
	v_mov_b32_e32 v39, v32
	v_mov_b32_e32 v40, v32
	v_mov_b32_e32 v41, v32
	v_mov_b32_e32 v42, v32
	v_mov_b32_e32 v43, v32
	v_mov_b32_e32 v44, v32
	v_mov_b32_e32 v45, v32
	v_mov_b32_e32 v46, v32
	v_mov_b32_e32 v47, v32
	v_pk_add_f32 v[64:65], v[64:65], v[148:149] op_sel_hi:[1,0] neg_lo:[0,1] neg_hi:[0,1]
	v_pk_add_f32 v[48:49], v[48:49], v[148:149] op_sel_hi:[1,0] neg_lo:[0,1] neg_hi:[0,1]
	v_pk_add_f32 v[66:67], v[66:67], v[148:149] op_sel_hi:[1,0] neg_lo:[0,1] neg_hi:[0,1]
	v_pk_add_f32 v[50:51], v[50:51], v[148:149] op_sel_hi:[1,0] neg_lo:[0,1] neg_hi:[0,1]
	v_pk_add_f32 v[68:69], v[68:69], v[148:149] op_sel_hi:[1,0] neg_lo:[0,1] neg_hi:[0,1]
	v_pk_add_f32 v[52:53], v[52:53], v[148:149] op_sel_hi:[1,0] neg_lo:[0,1] neg_hi:[0,1]
	v_pk_add_f32 v[70:71], v[70:71], v[148:149] op_sel_hi:[1,0] neg_lo:[0,1] neg_hi:[0,1]
	v_pk_add_f32 v[54:55], v[54:55], v[148:149] op_sel_hi:[1,0] neg_lo:[0,1] neg_hi:[0,1]
	v_pk_add_f32 v[72:73], v[72:73], v[148:149] op_sel_hi:[1,0] neg_lo:[0,1] neg_hi:[0,1]
	v_pk_add_f32 v[56:57], v[56:57], v[148:149] op_sel_hi:[1,0] neg_lo:[0,1] neg_hi:[0,1]
	v_pk_add_f32 v[74:75], v[74:75], v[148:149] op_sel_hi:[1,0] neg_lo:[0,1] neg_hi:[0,1]
	v_pk_add_f32 v[58:59], v[58:59], v[148:149] op_sel_hi:[1,0] neg_lo:[0,1] neg_hi:[0,1]
	v_pk_add_f32 v[76:77], v[76:77], v[148:149] op_sel_hi:[1,0] neg_lo:[0,1] neg_hi:[0,1]
	v_pk_add_f32 v[60:61], v[60:61], v[148:149] op_sel_hi:[1,0] neg_lo:[0,1] neg_hi:[0,1]
	v_pk_add_f32 v[78:79], v[78:79], v[148:149] op_sel_hi:[1,0] neg_lo:[0,1] neg_hi:[0,1]
	v_pk_add_f32 v[62:63], v[62:63], v[148:149] op_sel_hi:[1,0] neg_lo:[0,1] neg_hi:[0,1]
	v_pk_mul_f32 v[30:31], v[30:31], v[160:161] op_sel_hi:[1,0]
	v_pk_mul_f32 v[28:29], v[28:29], v[160:161] op_sel_hi:[1,0]
	v_pk_mul_f32 v[26:27], v[26:27], v[160:161] op_sel_hi:[1,0]
	v_pk_mul_f32 v[24:25], v[24:25], v[160:161] op_sel_hi:[1,0]
	v_pk_mul_f32 v[22:23], v[22:23], v[160:161] op_sel_hi:[1,0]
	v_pk_mul_f32 v[20:21], v[20:21], v[160:161] op_sel_hi:[1,0]
	v_pk_mul_f32 v[18:19], v[18:19], v[160:161] op_sel_hi:[1,0]
	v_pk_mul_f32 v[16:17], v[16:17], v[160:161] op_sel_hi:[1,0]
	v_pk_mul_f32 v[14:15], v[14:15], v[160:161] op_sel_hi:[1,0]
	v_pk_mul_f32 v[12:13], v[12:13], v[160:161] op_sel_hi:[1,0]
	v_pk_mul_f32 v[10:11], v[10:11], v[160:161] op_sel_hi:[1,0]
	v_pk_mul_f32 v[8:9], v[8:9], v[160:161] op_sel_hi:[1,0]
	v_pk_mul_f32 v[6:7], v[6:7], v[160:161] op_sel_hi:[1,0]
	v_pk_mul_f32 v[4:5], v[4:5], v[160:161] op_sel_hi:[1,0]
	v_pk_mul_f32 v[2:3], v[2:3], v[160:161] op_sel_hi:[1,0]
	v_pk_mul_f32 v[0:1], v[0:1], v[160:161] op_sel_hi:[1,0]
	v_pk_mul_f32 v[152:153], v[152:153], v[160:161] op_sel_hi:[1,0]
	v_pk_mul_f32 v[150:151], v[150:151], v[160:161] op_sel_hi:[1,0]
; #define AT_QK_LD0(kb_) do { if constexpr (NEGM) { const LAS unsigned char* kbp_ = Kl + (kb_) * KBUF + r32 * KROWB + hi * 16; AT_KLD2(0); __builtin_amdgcn_sched_barrier(0); } } while (0)
; template <int DQK, int DV, int RH, bool NEGM> ...
;     ...
;     const int NT = nkv / 64;
;     AT_GLOAD(0); AT_LSTORE(0, 0); __syncthreads();
;     int vs_prev = 2, vs_cur = 0, vs_next = 1;
;     if (!grpB) {
;         for (int t = 0; t < NT; ++t) {
;             const int kb = t & 1;
;             if (t + 1 < NT) AT_GLOAD(t + 1);
;             f32x16 p[RH][2];
;             AT_QK_LD0(kb); AT_QK(kb); AT_VLOAD(vs_cur); AT_SOFTMAX(); AT_PV(vs_cur);
;             if (t + 1 < NT) AT_LSTORE(kb ^ 1, vs_next);
;             __syncthreads();
.Lmla_norescale_o:
	v_exp_f32_e32 v160, v64
	v_exp_f32_e32 v161, v65
	v_exp_f32_e32 v64, v66
	v_exp_f32_e32 v65, v67
	v_exp_f32_e32 v68, v68
	v_exp_f32_e32 v69, v69
	v_exp_f32_e32 v66, v70
	v_exp_f32_e32 v67, v71
	v_cvt_pk_bf16_f32 v176, v160, v161
	v_cvt_pk_bf16_f32 v177, v64, v65
	v_cvt_pk_bf16_f32 v178, v68, v69
	v_cvt_pk_bf16_f32 v179, v66, v67
	v_exp_f32_e32 v70, v74
	v_exp_f32_e32 v71, v75
	s_waitcnt lgkmcnt(0)
	v_mfma_f32_32x32x16_bf16 v[16:31], v[136:139], v[176:179], v[16:31]
	v_exp_f32_e32 v136, v72
	v_exp_f32_e32 v137, v73
	v_exp_f32_e32 v74, v76
	v_exp_f32_e32 v75, v77
	v_exp_f32_e32 v72, v78
	v_exp_f32_e32 v73, v79
	v_exp_f32_e32 v76, v48
	v_mfma_f32_32x32x16_bf16 v[0:15], v[144:147], v[176:179], v[0:15]
	v_cvt_pk_bf16_f32 v144, v136, v137
	v_cvt_pk_bf16_f32 v145, v70, v71
	v_cvt_pk_bf16_f32 v146, v74, v75
	v_cvt_pk_bf16_f32 v147, v72, v73
	v_exp_f32_e32 v77, v49
	v_exp_f32_e32 v48, v50
	v_exp_f32_e32 v49, v51
	v_mfma_f32_32x32x16_bf16 v[16:31], v[124:127], v[144:147], v[16:31]
	v_exp_f32_e32 v52, v52
	v_exp_f32_e32 v53, v53
	v_exp_f32_e32 v50, v54
	v_exp_f32_e32 v51, v55
	v_cvt_pk_bf16_f32 v124, v76, v77
	v_cvt_pk_bf16_f32 v125, v48, v49
	v_cvt_pk_bf16_f32 v126, v52, v53
	v_mfma_f32_32x32x16_bf16 v[0:15], v[140:143], v[144:147], v[0:15]
	v_cvt_pk_bf16_f32 v127, v50, v51
	v_exp_f32_e32 v78, v56
	v_exp_f32_e32 v79, v57
	v_exp_f32_e32 v54, v58
	v_exp_f32_e32 v55, v59
	v_exp_f32_e32 v58, v60
	v_exp_f32_e32 v59, v61
	v_mfma_f32_32x32x16_bf16 v[16:31], v[132:135], v[124:127], v[16:31]
	v_exp_f32_e32 v56, v62
	v_exp_f32_e32 v57, v63
	v_cvt_pk_bf16_f32 v60, v78, v79
	v_cvt_pk_bf16_f32 v61, v54, v55
	v_cvt_pk_bf16_f32 v62, v58, v59
	v_cvt_pk_bf16_f32 v63, v56, v57
	v_mfma_f32_32x32x16_bf16 v[0:15], v[128:131], v[124:127], v[0:15]
	v_mfma_f32_32x32x16_bf16 v[16:31], v[120:123], v[60:63], v[16:31]
	v_mfma_f32_32x32x16_bf16 v[0:15], v[116:119], v[60:63], v[0:15]
	s_waitcnt vmcnt(1)
	ds_write_b128 v244, v[104:107]
	s_mov_b64 exec, s[8:9]
	ds_write_b128 v245, v[108:111]
	s_mov_b64 exec, -1
	v_pk_add_f32 v[48:49], v[64:65], v[48:49]
	v_pk_add_f32 v[60:61], v[160:161], v[76:77]
	v_pk_add_f32 v[48:49], v[152:153], v[48:49]
	v_pk_add_f32 v[50:51], v[66:67], v[50:51]
	v_pk_add_f32 v[60:61], v[150:151], v[60:61]
	v_pk_add_f32 v[52:53], v[68:69], v[52:53]
	v_pk_add_f32 v[48:49], v[50:51], v[48:49]
	v_pk_add_f32 v[50:51], v[70:71], v[54:55]
	v_pk_add_f32 v[52:53], v[52:53], v[60:61]
	v_pk_add_f32 v[60:61], v[136:137], v[78:79]
	v_pk_add_f32 v[48:49], v[50:51], v[48:49]
	v_pk_add_f32 v[50:51], v[72:73], v[56:57]
	s_mul_i32 s21, s42, 0x2400
	s_add_i32 s40, s42, 1
	v_pk_add_f32 v[52:53], v[60:61], v[52:53]
	v_pk_add_f32 v[58:59], v[74:75], v[58:59]
	v_pk_add_f32 v[152:153], v[50:51], v[48:49]
	v_add_u32_e32 v48, s21, v243
	s_cmp_lg_u32 s42, 2
	v_pk_add_f32 v[150:151], v[58:59], v[52:53]
	s_cselect_b32 s40, s40, 0
	s_cmp_lg_u32 s43, 63
	s_waitcnt vmcnt(0)
	ds_write2_b64 v48, v[112:113], v[114:115] offset1:2
	s_waitcnt lgkmcnt(0)
	s_barrier
	s_mov_b32 s21, s42
	s_mov_b32 s42, s40
	global_load_dwordx4 v[104:107], v154, s[98:99]
	s_mov_b64 exec, s[8:9]
	global_load_dwordx4 v[108:111], v156, s[98:99]
	s_mov_b64 exec, -1
	global_load_dwordx4 v[112:115], v158, s[100:101]
	s_add_u32 s98, s98, 0x18000
	s_addc_u32 s99, s99, 0
	s_add_u32 s100, s100, 0x80
	s_addc_u32 s101, s101, 0
	ds_read_b128 v[48:51], v169
	ds_read_b128 v[52:55], v169 offset:32
	ds_read_b128 v[116:119], v169 offset:6656
	ds_read_b128 v[120:123], v169 offset:6688
	s_waitcnt lgkmcnt(3)
	v_mfma_f32_32x32x16_bf16 v[64:79], v[48:51], v[100:103], v[32:47]
	ds_read_b128 v[124:127], v169 offset:64
	ds_read_b128 v[128:131], v169 offset:96
	ds_read_b128 v[132:135], v169 offset:6720
	ds_read_b128 v[136:139], v169 offset:6752
	s_waitcnt lgkmcnt(4)
	v_mfma_f32_32x32x16_bf16 v[64:79], v[52:55], v[96:99], v[64:79]
	v_mfma_f32_32x32x16_bf16 v[48:63], v[116:119], v[100:103], v[32:47]
	v_mfma_f32_32x32x16_bf16 v[48:63], v[120:123], v[96:99], v[48:63]
	s_waitcnt lgkmcnt(1)
	v_mfma_f32_32x32x16_bf16 v[64:79], v[124:127], v[92:95], v[64:79]
	v_mfma_f32_32x32x16_bf16 v[48:63], v[132:135], v[92:95], v[48:63]
	v_mfma_f32_32x32x16_bf16 v[64:79], v[128:131], v[88:91], v[64:79]
	ds_read_b128 v[116:119], v169 offset:128
	ds_read_b128 v[120:123], v169 offset:160
	ds_read_b128 v[128:131], v169 offset:6784
	ds_read_b128 v[176:179], v169 offset:6816
	s_waitcnt lgkmcnt(3)
	v_mfma_f32_32x32x16_bf16 v[48:63], v[136:139], v[88:91], v[48:63]
	v_mfma_f32_32x32x16_bf16 v[64:79], v[116:119], v[84:87], v[64:79]
	s_mulk_i32 s21, 0x2400
	v_add_u32_e32 v116, s21, v170
	ds_read_b128 v[136:139], v116 offset:26624
	ds_read_b128 v[124:127], v116 offset:26656
	s_waitcnt lgkmcnt(3)
	v_mfma_f32_32x32x16_bf16 v[48:63], v[128:131], v[84:87], v[48:63]
	v_mfma_f32_32x32x16_bf16 v[64:79], v[120:123], v[80:83], v[64:79]
	ds_read_b128 v[132:135], v116 offset:26688
	ds_read_b128 v[120:123], v116 offset:26720
	ds_read_b128 v[144:147], v116 offset:31232
	ds_read_b128 v[140:143], v116 offset:31264
	ds_read_b128 v[128:131], v116 offset:31296
	ds_read_b128 v[116:119], v116 offset:31328
	s_waitcnt lgkmcnt(8)
	v_mfma_f32_32x32x16_bf16 v[48:63], v[176:179], v[80:83], v[48:63]
	s_add_i32 s43, s43, 1
	s_nop 10
	v_max_f32_e32 v148, v64, v48
	v_max_f32_e32 v160, v65, v49
	v_max_f32_e32 v161, v67, v51
	v_max3_f32 v176, v66, v50, v70
	v_max3_f32 v161, v161, v71, v55
	v_max3_f32 v148, v148, v68, v52
	v_max3_f32 v160, v160, v69, v53
	v_max3_f32 v176, v176, v54, v74
	v_max3_f32 v161, v161, v75, v59
	v_max3_f32 v148, v148, v72, v56
	v_max3_f32 v160, v160, v73, v57
	v_max3_f32 v176, v176, v58, v78
	v_max3_f32 v161, v161, v79, v63
	v_max3_f32 v148, v148, v76, v60
	v_max3_f32 v160, v160, v77, v61
	v_max3_f32 v161, v176, v62, v161
	v_max3_f32 v148, v148, v160, v161
	v_mov_b32_e32 v160, v148
	s_nop 1
	v_permlane32_swap_b32_e32 v148, v160
	v_max_f32_e32 v148, v148, v160
	v_cmp_lt_f32_e32 vcc, s59, v148
	s_cbranch_vccz .Lmla_norescale_e
	v_max_f32_e32 v32, v148, v148
	v_max_f32_e32 v148, 0, v32
	v_exp_f32_e64 v160, -v148
	v_add_f32_e32 v168, v168, v148
	v_xor_b32_e32 v32, 0x80000000, v168
	v_mov_b32_e32 v33, v32
	v_mov_b32_e32 v34, v32
	v_mov_b32_e32 v35, v32
	v_mov_b32_e32 v36, v32
	v_mov_b32_e32 v37, v32
	v_mov_b32_e32 v38, v32
	v_mov_b32_e32 v39, v32
	v_mov_b32_e32 v40, v32
	v_mov_b32_e32 v41, v32
	v_mov_b32_e32 v42, v32
	v_mov_b32_e32 v43, v32
	v_mov_b32_e32 v44, v32
	v_mov_b32_e32 v45, v32
	v_mov_b32_e32 v46, v32
	v_mov_b32_e32 v47, v32
	v_pk_add_f32 v[64:65], v[64:65], v[148:149] op_sel_hi:[1,0] neg_lo:[0,1] neg_hi:[0,1]
	v_pk_add_f32 v[48:49], v[48:49], v[148:149] op_sel_hi:[1,0] neg_lo:[0,1] neg_hi:[0,1]
	v_pk_add_f32 v[66:67], v[66:67], v[148:149] op_sel_hi:[1,0] neg_lo:[0,1] neg_hi:[0,1]
	v_pk_add_f32 v[50:51], v[50:51], v[148:149] op_sel_hi:[1,0] neg_lo:[0,1] neg_hi:[0,1]
	v_pk_add_f32 v[68:69], v[68:69], v[148:149] op_sel_hi:[1,0] neg_lo:[0,1] neg_hi:[0,1]
	v_pk_add_f32 v[52:53], v[52:53], v[148:149] op_sel_hi:[1,0] neg_lo:[0,1] neg_hi:[0,1]
	v_pk_add_f32 v[70:71], v[70:71], v[148:149] op_sel_hi:[1,0] neg_lo:[0,1] neg_hi:[0,1]
	v_pk_add_f32 v[54:55], v[54:55], v[148:149] op_sel_hi:[1,0] neg_lo:[0,1] neg_hi:[0,1]
	v_pk_add_f32 v[72:73], v[72:73], v[148:149] op_sel_hi:[1,0] neg_lo:[0,1] neg_hi:[0,1]
	v_pk_add_f32 v[56:57], v[56:57], v[148:149] op_sel_hi:[1,0] neg_lo:[0,1] neg_hi:[0,1]
	v_pk_add_f32 v[74:75], v[74:75], v[148:149] op_sel_hi:[1,0] neg_lo:[0,1] neg_hi:[0,1]
	v_pk_add_f32 v[58:59], v[58:59], v[148:149] op_sel_hi:[1,0] neg_lo:[0,1] neg_hi:[0,1]
	v_pk_add_f32 v[76:77], v[76:77], v[148:149] op_sel_hi:[1,0] neg_lo:[0,1] neg_hi:[0,1]
	v_pk_add_f32 v[60:61], v[60:61], v[148:149] op_sel_hi:[1,0] neg_lo:[0,1] neg_hi:[0,1]
	v_pk_add_f32 v[78:79], v[78:79], v[148:149] op_sel_hi:[1,0] neg_lo:[0,1] neg_hi:[0,1]
	v_pk_add_f32 v[62:63], v[62:63], v[148:149] op_sel_hi:[1,0] neg_lo:[0,1] neg_hi:[0,1]
	v_pk_mul_f32 v[30:31], v[30:31], v[160:161] op_sel_hi:[1,0]
	v_pk_mul_f32 v[28:29], v[28:29], v[160:161] op_sel_hi:[1,0]
	v_pk_mul_f32 v[26:27], v[26:27], v[160:161] op_sel_hi:[1,0]
	v_pk_mul_f32 v[24:25], v[24:25], v[160:161] op_sel_hi:[1,0]
	v_pk_mul_f32 v[22:23], v[22:23], v[160:161] op_sel_hi:[1,0]
	v_pk_mul_f32 v[20:21], v[20:21], v[160:161] op_sel_hi:[1,0]
	v_pk_mul_f32 v[18:19], v[18:19], v[160:161] op_sel_hi:[1,0]
	v_pk_mul_f32 v[16:17], v[16:17], v[160:161] op_sel_hi:[1,0]
	v_pk_mul_f32 v[14:15], v[14:15], v[160:161] op_sel_hi:[1,0]
	v_pk_mul_f32 v[12:13], v[12:13], v[160:161] op_sel_hi:[1,0]
	v_pk_mul_f32 v[10:11], v[10:11], v[160:161] op_sel_hi:[1,0]
	v_pk_mul_f32 v[8:9], v[8:9], v[160:161] op_sel_hi:[1,0]
	v_pk_mul_f32 v[6:7], v[6:7], v[160:161] op_sel_hi:[1,0]
	v_pk_mul_f32 v[4:5], v[4:5], v[160:161] op_sel_hi:[1,0]
	v_pk_mul_f32 v[2:3], v[2:3], v[160:161] op_sel_hi:[1,0]
	v_pk_mul_f32 v[0:1], v[0:1], v[160:161] op_sel_hi:[1,0]
	v_pk_mul_f32 v[152:153], v[152:153], v[160:161] op_sel_hi:[1,0]
	v_pk_mul_f32 v[150:151], v[150:151], v[160:161] op_sel_hi:[1,0]
; #define AT_QK_LD0(kb_) do { if constexpr (NEGM) { const LAS unsigned char* kbp_ = Kl + (kb_) * KBUF + r32 * KROWB + hi * 16; AT_KLD2(0); __builtin_amdgcn_sched_barrier(0); } } while (0)
; template <int DQK, int DV, int RH, bool NEGM> ...
;     ...
;     const int NT = nkv / 64;
;     AT_GLOAD(0); AT_LSTORE(0, 0); __syncthreads();
;     int vs_prev = 2, vs_cur = 0, vs_next = 1;
;     if (!grpB) {
;         for (int t = 0; t < NT; ++t) {
;             const int kb = t & 1;
;             if (t + 1 < NT) AT_GLOAD(t + 1);
;             f32x16 p[RH][2];
;             AT_QK_LD0(kb); AT_QK(kb); AT_VLOAD(vs_cur); AT_SOFTMAX(); AT_PV(vs_cur);
;             if (t + 1 < NT) AT_LSTORE(kb ^ 1, vs_next);
;             __syncthreads();
;             vs_prev = vs_cur; vs_cur = vs_next; vs_next = (vs_next == 2) ? 0 : vs_next + 1;
.Lmla_norescale_e:
	v_exp_f32_e32 v160, v64
	v_exp_f32_e32 v161, v65
	v_exp_f32_e32 v64, v66
	v_exp_f32_e32 v65, v67
	v_exp_f32_e32 v68, v68
	v_exp_f32_e32 v69, v69
	v_exp_f32_e32 v66, v70
	v_exp_f32_e32 v67, v71
	v_cvt_pk_bf16_f32 v176, v160, v161
	v_cvt_pk_bf16_f32 v177, v64, v65
	v_cvt_pk_bf16_f32 v178, v68, v69
	v_cvt_pk_bf16_f32 v179, v66, v67
	v_exp_f32_e32 v70, v74
	v_exp_f32_e32 v71, v75
	s_waitcnt lgkmcnt(0)
	v_mfma_f32_32x32x16_bf16 v[16:31], v[136:139], v[176:179], v[16:31]
	v_exp_f32_e32 v136, v72
	v_exp_f32_e32 v137, v73
	v_exp_f32_e32 v74, v76
	v_exp_f32_e32 v75, v77
	v_exp_f32_e32 v72, v78
	v_exp_f32_e32 v73, v79
	v_exp_f32_e32 v76, v48
	v_mfma_f32_32x32x16_bf16 v[0:15], v[144:147], v[176:179], v[0:15]
	v_cvt_pk_bf16_f32 v144, v136, v137
	v_cvt_pk_bf16_f32 v145, v70, v71
	v_cvt_pk_bf16_f32 v146, v74, v75
	v_cvt_pk_bf16_f32 v147, v72, v73
	v_exp_f32_e32 v77, v49
	v_exp_f32_e32 v48, v50
	v_exp_f32_e32 v49, v51
	v_mfma_f32_32x32x16_bf16 v[16:31], v[124:127], v[144:147], v[16:31]
	v_exp_f32_e32 v52, v52
	v_exp_f32_e32 v53, v53
	v_exp_f32_e32 v50, v54
	v_exp_f32_e32 v51, v55
	v_cvt_pk_bf16_f32 v124, v76, v77
	v_cvt_pk_bf16_f32 v125, v48, v49
	v_cvt_pk_bf16_f32 v126, v52, v53
	v_mfma_f32_32x32x16_bf16 v[0:15], v[140:143], v[144:147], v[0:15]
	v_cvt_pk_bf16_f32 v127, v50, v51
	v_exp_f32_e32 v78, v56
	v_exp_f32_e32 v79, v57
	v_exp_f32_e32 v54, v58
	v_exp_f32_e32 v55, v59
	v_exp_f32_e32 v58, v60
	v_exp_f32_e32 v59, v61
	v_mfma_f32_32x32x16_bf16 v[16:31], v[132:135], v[124:127], v[16:31]
	v_exp_f32_e32 v56, v62
	v_exp_f32_e32 v57, v63
	v_cvt_pk_bf16_f32 v60, v78, v79
	v_cvt_pk_bf16_f32 v61, v54, v55
	v_cvt_pk_bf16_f32 v62, v58, v59
	v_cvt_pk_bf16_f32 v63, v56, v57
	v_mfma_f32_32x32x16_bf16 v[0:15], v[128:131], v[124:127], v[0:15]
	v_mfma_f32_32x32x16_bf16 v[16:31], v[120:123], v[60:63], v[16:31]
	v_mfma_f32_32x32x16_bf16 v[0:15], v[116:119], v[60:63], v[0:15]
	s_waitcnt vmcnt(1)
	ds_write_b128 v244, v[104:107] offset:13312
	s_mov_b64 exec, s[8:9]
	ds_write_b128 v245, v[108:111] offset:13312
	s_mov_b64 exec, -1
	v_pk_add_f32 v[48:49], v[64:65], v[48:49]
	v_pk_add_f32 v[60:61], v[160:161], v[76:77]
	v_pk_add_f32 v[48:49], v[152:153], v[48:49]
	v_pk_add_f32 v[50:51], v[66:67], v[50:51]
	v_pk_add_f32 v[60:61], v[150:151], v[60:61]
	v_pk_add_f32 v[52:53], v[68:69], v[52:53]
	v_pk_add_f32 v[48:49], v[50:51], v[48:49]
	v_pk_add_f32 v[50:51], v[70:71], v[54:55]
	v_pk_add_f32 v[52:53], v[52:53], v[60:61]
	v_pk_add_f32 v[60:61], v[136:137], v[78:79]
	v_pk_add_f32 v[48:49], v[50:51], v[48:49]
	v_pk_add_f32 v[50:51], v[72:73], v[56:57]
	s_mul_i32 s21, s42, 0x2400
	s_add_i32 s40, s42, 1
	v_pk_add_f32 v[52:53], v[60:61], v[52:53]
	v_pk_add_f32 v[58:59], v[74:75], v[58:59]
	v_pk_add_f32 v[152:153], v[50:51], v[48:49]
	v_add_u32_e32 v48, s21, v243
	s_cmp_lg_u32 s42, 2
	v_pk_add_f32 v[150:151], v[58:59], v[52:53]
	s_cselect_b32 s40, s40, 0
	s_cmp_lg_u32 s43, 63
	s_waitcnt vmcnt(0)
	ds_write2_b64 v48, v[112:113], v[114:115] offset1:2
	s_waitcnt lgkmcnt(0)
	s_barrier
	s_cbranch_scc1 .Lmla_loop
	ds_read_b128 v[64:67], v169 offset:13312
	ds_read_b128 v[68:71], v169 offset:13344
	ds_read_b128 v[72:75], v169 offset:19968
	ds_read_b128 v[76:79], v169 offset:20000
	s_waitcnt lgkmcnt(3)
	v_mfma_f32_32x32x16_bf16 v[48:63], v[64:67], v[100:103], v[32:47]
	ds_read_b128 v[64:67], v169 offset:13376
	ds_read_b128 v[104:107], v169 offset:13408
	ds_read_b128 v[108:111], v169 offset:20032
	ds_read_b128 v[112:115], v169 offset:20064
	s_waitcnt lgkmcnt(6)
	v_mfma_f32_32x32x16_bf16 v[48:63], v[68:71], v[96:99], v[48:63]
	s_waitcnt lgkmcnt(5)
	v_mfma_f32_32x32x16_bf16 v[32:47], v[72:75], v[100:103], v[32:47]
	s_waitcnt lgkmcnt(4)
	v_mfma_f32_32x32x16_bf16 v[32:47], v[76:79], v[96:99], v[32:47]
	s_waitcnt lgkmcnt(3)
	v_mfma_f32_32x32x16_bf16 v[48:63], v[64:67], v[92:95], v[48:63]
	ds_read_b128 v[64:67], v169 offset:13440
	ds_read_b128 v[68:71], v169 offset:13472
	ds_read_b128 v[72:75], v169 offset:20096
	ds_read_b128 v[76:79], v169 offset:20128
	s_waitcnt lgkmcnt(5)
	v_mfma_f32_32x32x16_bf16 v[32:47], v[108:111], v[92:95], v[32:47]
	v_mfma_f32_32x32x16_bf16 v[48:63], v[104:107], v[88:91], v[48:63]
	s_waitcnt lgkmcnt(4)
	v_mfma_f32_32x32x16_bf16 v[32:47], v[112:115], v[88:91], v[32:47]
	s_waitcnt lgkmcnt(3)
	v_mfma_f32_32x32x16_bf16 v[48:63], v[64:67], v[84:87], v[48:63]
	v_add3_u32 v64, v167, s21, v173
	v_add_u32_e32 v65, 0x6800, v64
	ds_read_b128 v[108:111], v65
	ds_read_b128 v[104:107], v65 offset:32
	ds_read_b128 v[96:99], v65 offset:64
	ds_read_b128 v[88:91], v65 offset:96
	s_waitcnt lgkmcnt(5)
	v_mfma_f32_32x32x16_bf16 v[32:47], v[72:75], v[84:87], v[32:47]
	ds_read_b128 v[112:115], v65 offset:4608
	ds_read_b128 v[100:103], v65 offset:4640
	ds_read_b128 v[92:95], v65 offset:4672
	ds_read_b128 v[84:87], v65 offset:4704
	v_mfma_f32_32x32x16_bf16 v[48:63], v[68:71], v[80:83], v[48:63]
	s_waitcnt lgkmcnt(8)
	v_mfma_f32_32x32x16_bf16 v[32:47], v[76:79], v[80:83], v[32:47]
	s_nop 11
	v_max_f32_e32 v64, v32, v32
	v_max_f32_e32 v65, v48, v48
	v_max_f32_e32 v64, v65, v64
	v_max_f32_e32 v65, v33, v33
	v_max_f32_e32 v66, v49, v49
	v_max_f32_e32 v65, v66, v65
	v_max_f32_e32 v66, v35, v35
	v_max_f32_e32 v67, v51, v51
	v_max_f32_e32 v66, v67, v66
	v_max3_f32 v67, v50, v34, v54
	v_max3_f32 v66, v66, v55, v39
	v_max3_f32 v64, v64, v52, v36
	v_max3_f32 v65, v65, v53, v37
	v_max3_f32 v67, v67, v38, v58
	v_max3_f32 v66, v66, v59, v43
	v_max3_f32 v64, v64, v56, v40
	v_max3_f32 v65, v65, v57, v41
	v_max3_f32 v67, v67, v42, v62
	v_max3_f32 v66, v66, v63, v47
	v_max3_f32 v64, v64, v60, v44
	v_max3_f32 v65, v65, v61, v45
	v_max3_f32 v66, v67, v46, v66
	v_max3_f32 v64, v64, v65, v66
	v_mov_b32_e32 v65, v64
	s_nop 1
	v_permlane32_swap_b32_e32 v64, v65
	v_max_f32_e32 v65, v65, v65
	v_max_f32_e32 v64, v64, v64
	v_max_f32_e32 v64, v64, v65
	v_cmp_lt_f32_e32 vcc, s59, v64
	s_cbranch_vccnz .LBB0_861
	v_mov_b32_e32 v64, v151
	v_mov_b32_e32 v151, v152
	v_mov_b32_e32 v65, v153
	s_branch .LBB0_862

; __global__ void __launch_bounds__(512, 2) fwd_mega(Args a) {
	.amdhsa_kernel _Z8fwd_mega4Args
		.amdhsa_group_segment_fixed_size 0
		.amdhsa_private_segment_fixed_size 0
		.amdhsa_kernarg_size 496
		.amdhsa_user_sgpr_count 2
		.amdhsa_user_sgpr_dispatch_ptr 0
		.amdhsa_user_sgpr_queue_ptr 0
		.amdhsa_user_sgpr_kernarg_segment_ptr 1
		.amdhsa_user_sgpr_dispatch_id 0
		.amdhsa_user_sgpr_kernarg_preload_length 0
		.amdhsa_user_sgpr_kernarg_preload_offset 0
		.amdhsa_user_sgpr_private_segment_size 0
		.amdhsa_uses_dynamic_stack 0
		.amdhsa_enable_private_segment 0
		.amdhsa_system_sgpr_workgroup_id_x 1
		.amdhsa_system_sgpr_workgroup_id_y 0
		.amdhsa_system_sgpr_workgroup_id_z 0
		.amdhsa_system_sgpr_workgroup_info 0
		.amdhsa_system_vgpr_workitem_id 2
		.amdhsa_next_free_vgpr 246
		.amdhsa_next_free_sgpr 102
		.amdhsa_accum_offset 248
		.amdhsa_reserve_vcc 1
		.amdhsa_float_round_mode_32 0
		.amdhsa_float_round_mode_16_64 0
		.amdhsa_float_denorm_mode_32 3
		.amdhsa_float_denorm_mode_16_64 3
		.amdhsa_dx10_clamp 1
		.amdhsa_ieee_mode 1
		.amdhsa_fp16_overflow 0
		.amdhsa_tg_split 0
		.amdhsa_exception_fp_ieee_invalid_op 0
		.amdhsa_exception_fp_denorm_src 0
		.amdhsa_exception_fp_ieee_div_zero 0
		.amdhsa_exception_fp_ieee_overflow 0
		.amdhsa_exception_fp_ieee_underflow 0
		.amdhsa_exception_fp_ieee_inexact 0
		.amdhsa_exception_int_div_zero 0
	.end_amdhsa_kernel

; __global__ void __launch_bounds__(512, 2) fwd_mega(Args a) {
.Lfunc_end0:
	.size	_Z8fwd_mega4Args, .Lfunc_end0-_Z8fwd_mega4Args
	.set _Z8fwd_mega4Args.num_vgpr, 246
	.set _Z8fwd_mega4Args.num_agpr, 0
	.set _Z8fwd_mega4Args.numbered_sgpr, 98
	.set _Z8fwd_mega4Args.num_named_barrier, 0
	.set _Z8fwd_mega4Args.private_seg_size, 0
	.set _Z8fwd_mega4Args.uses_vcc, 1
	.set _Z8fwd_mega4Args.uses_flat_scratch, 0
	.set _Z8fwd_mega4Args.has_dyn_sized_stack, 0
	.set _Z8fwd_mega4Args.has_recursion, 0
	.set _Z8fwd_mega4Args.has_indirect_call, 0

amdhsa.kernels:
  - .agpr_count:     0
    .args:
      - .offset:         0
        .size:           240
        .value_kind:     by_value
      - .offset:         240
        .size:           4
        .value_kind:     hidden_block_count_x
      - .offset:         244
        .size:           4
        .value_kind:     hidden_block_count_y
      - .offset:         248
        .size:           4
        .value_kind:     hidden_block_count_z
      - .offset:         252
        .size:           2
        .value_kind:     hidden_group_size_x
      - .offset:         254
        .size:           2
        .value_kind:     hidden_group_size_y
      - .offset:         256
        .size:           2
        .value_kind:     hidden_group_size_z
      - .offset:         258
        .size:           2
        .value_kind:     hidden_remainder_x
      - .offset:         260
        .size:           2
        .value_kind:     hidden_remainder_y
      - .offset:         262
        .size:           2
        .value_kind:     hidden_remainder_z
      - .offset:         280
        .size:           8
        .value_kind:     hidden_global_offset_x
      - .offset:         288
        .size:           8
        .value_kind:     hidden_global_offset_y
      - .offset:         296
        .size:           8
        .value_kind:     hidden_global_offset_z
      - .offset:         304
        .size:           2
        .value_kind:     hidden_grid_dims
      - .offset:         328
        .size:           8
        .value_kind:     hidden_multigrid_sync_arg
      - .offset:         360
        .size:           4
        .value_kind:     hidden_dynamic_lds_size
    .group_segment_fixed_size: 0
    .kernarg_segment_align: 8
    .kernarg_segment_size: 496
    .language:       OpenCL C
    .language_version:
      - 2
      - 0
    .max_flat_workgroup_size: 512
    .name:           _Z8fwd_mega4Args
    .private_segment_fixed_size: 0
    .sgpr_count:     108
    .sgpr_spill_count: 6
    .symbol:         _Z8fwd_mega4Args.kd
    .uniform_work_group_size: 1
    .uses_dynamic_stack: false
    .vgpr_count:     246
    .vgpr_spill_count: 0
    .wavefront_size: 64
